# acquire-side buffer_inv sc1 of the three grid-wide seams issued at the arrive (overlaps the wait) instead of after the spin
# speedup vs baseline: 1.0092x; 1.0011x over previous
; __device__ __forceinline__ unsigned xb_ld(unsigned* p)              { return __hip_atomic_load(p, __ATOMIC_RELAXED, __HIP_MEMORY_SCOPE_AGENT); }
; __device__ __forceinline__ unsigned xb_add(unsigned* p, unsigned v) { return __hip_atomic_fetch_add(p, v, __ATOMIC_RELAXED, __HIP_MEMORY_SCOPE_AGENT); }
; #define XB_SPIN(cond, bar) do { unsigned _sp = 0; while (cond) { __builtin_amdgcn_s_sleep(1); \
;     if ((++_sp & 255u) == 0u) { if (xb_ld(&(bar)[XB_TMO])) break; if (_sp > XB_SPIN_CAP) { atomicAdd(&(bar)[XB_TMO], 1u); break; } } } } while (0)
; __device__ __forceinline__ void xcd_barrier(const XcdBarrier& b) {
;     ...
;         unsigned nloc = b.st[0], nx = b.st[1];
;         if (nloc == 0u) { xcd_barrier_complete(bar, b.x, nloc, nx); b.st[0] = nloc; b.st[1] = nx; }
;         const unsigned old = xb_add(&bar[XB_XSUB(b.x)], 1u);
;         const unsigned gen = old / nloc;
;         if (old + 1u == (gen + 1u) * nloc) {
;             __builtin_amdgcn_fence(__ATOMIC_RELEASE, "agent");
;             asm volatile("s_waitcnt vmcnt(0)" ::: "memory");
;             const unsigned og = xb_add(&bar[XB_TOP], 1u);
;             const unsigned tg = og / nx;
;             if (og + 1u == (tg + 1u) * nx) xb_add(&bar[XB_TOPGEN], 1u);
;             else XB_SPIN(xb_ld(&bar[XB_TOPGEN]) == tg, bar);
;             __builtin_amdgcn_fence(__ATOMIC_ACQUIRE, "agent");
;             xb_add(&bar[XB_XGEN(b.x)], 1u);
;             asm volatile("s_waitcnt vmcnt(0)" ::: "memory");
;         } else {
;             XB_SPIN(xb_ld(&bar[XB_XGEN(b.x)]) == gen, bar);
;             __builtin_amdgcn_fence(__ATOMIC_ACQUIRE, "agent");
;             asm volatile("s_waitcnt vmcnt(0)" ::: "memory");
.LBB0_115:
	s_or_b64 exec, exec, s[12:13]
	buffer_inv sc1
	v_cvt_f32_u32_e32 v4, v2
	s_waitcnt vmcnt(0)
	v_readfirstlane_b32 s10, v3
	v_sub_u32_e32 v3, 0, v2
	v_rcp_iflag_f32_e32 v4, v4
	v_add_u32_e32 v5, s10, v1
	v_mul_f32_e32 v4, 0x4f7ffffe, v4
	v_cvt_u32_f32_e32 v4, v4
	v_mul_lo_u32 v1, v3, v4
	v_mul_hi_u32 v1, v4, v1
	v_add_u32_e32 v1, v4, v1
	v_mul_hi_u32 v1, v5, v1
	v_mul_lo_u32 v3, v1, v2
	v_sub_u32_e32 v3, v5, v3
	v_add_u32_e32 v4, 1, v1
	v_cmp_ge_u32_e32 vcc, v3, v2
	s_nop 1
	v_cndmask_b32_e32 v1, v1, v4, vcc
	v_sub_u32_e32 v4, v3, v2
	v_cndmask_b32_e32 v3, v3, v4, vcc
	v_add_u32_e32 v4, 1, v1
	v_cmp_ge_u32_e32 vcc, v3, v2
	v_add_u32_e32 v3, 1, v5
	s_nop 0
	v_cndmask_b32_e32 v1, v1, v4, vcc
	v_mul_lo_u32 v4, v2, v1
	v_add_u32_e32 v2, v4, v2
	v_cmp_ne_u32_e32 vcc, v3, v2
	s_and_saveexec_b64 s[10:11], vcc
	s_xor_b64 s[10:11], exec, s[10:11]
	s_cbranch_execz .LBB0_129
	s_waitcnt lgkmcnt(0)
	v_mov_b32_e32 v0, 0x2000
	global_load_dword v0, v0, s[8:9] offset:1024 sc1
	s_add_u32 s16, s8, 0x2400
	s_addc_u32 s17, s9, 0
	s_waitcnt vmcnt(0)
	v_cmp_eq_u32_e32 vcc, v0, v1
	s_and_saveexec_b64 s[12:13], vcc
	s_cbranch_execz .LBB0_128
	s_add_u32 s14, s92, 0x4200
	s_addc_u32 s15, s93, 0
	s_mov_b32 s28, 1
	s_mov_b64 s[18:19], 0
	v_mov_b32_e32 v0, 0
	s_branch .LBB0_119

; __device__ __forceinline__ unsigned xb_ld(unsigned* p)              { return __hip_atomic_load(p, __ATOMIC_RELAXED, __HIP_MEMORY_SCOPE_AGENT); }
; __device__ __forceinline__ unsigned xb_add(unsigned* p, unsigned v) { return __hip_atomic_fetch_add(p, v, __ATOMIC_RELAXED, __HIP_MEMORY_SCOPE_AGENT); }
; #define XB_SPIN(cond, bar) do { unsigned _sp = 0; while (cond) { __builtin_amdgcn_s_sleep(1); \
;     if ((++_sp & 255u) == 0u) { if (xb_ld(&(bar)[XB_TMO])) break; if (_sp > XB_SPIN_CAP) { atomicAdd(&(bar)[XB_TMO], 1u); break; } } } } while (0)
; __device__ __forceinline__ void xcd_barrier(const XcdBarrier& b) {
;     ...
;         if (old + 1u == (gen + 1u) * nloc) {
;             __builtin_amdgcn_fence(__ATOMIC_RELEASE, "agent");
;             asm volatile("s_waitcnt vmcnt(0)" ::: "memory");
;             const unsigned og = xb_add(&bar[XB_TOP], 1u);
;             const unsigned tg = og / nx;
;             if (og + 1u == (tg + 1u) * nx) xb_add(&bar[XB_TOPGEN], 1u);
;             else XB_SPIN(xb_ld(&bar[XB_TOPGEN]) == tg, bar);
;             __builtin_amdgcn_fence(__ATOMIC_ACQUIRE, "agent");
;             xb_add(&bar[XB_XGEN(b.x)], 1u);
;             asm volatile("s_waitcnt vmcnt(0)" ::: "memory");
;         } else {
;             XB_SPIN(xb_ld(&bar[XB_XGEN(b.x)]) == gen, bar);
.LBB0_125:
	s_or_b64 exec, exec, s[18:19]
	s_xor_b64 s[16:17], s[20:21], -1
	s_and_saveexec_b64 s[18:19], s[16:17]
	s_xor_b64 s[18:19], exec, s[18:19]
	s_cbranch_execz .LBB0_128
	s_mov_b64 s[16:17], exec
	v_mbcnt_lo_u32_b32 v0, s16, 0
	v_mbcnt_hi_u32_b32 v0, s17, v0
	v_cmp_eq_u32_e32 vcc, 0, v0
	s_and_b64 s[18:19], exec, vcc
	s_mov_b64 exec, s[18:19]
	s_cbranch_execz .LBB0_128
	s_bcnt1_i32_b64 s16, s[16:17]
	v_mov_b32_e32 v0, 0
	v_mov_b32_e32 v1, s16
	global_atomic_add v0, v1, s[14:15]
.LBB0_128:
	s_or_b64 exec, exec, s[12:13]
	s_waitcnt vmcnt(0)
	s_waitcnt vmcnt(0)
.LBB0_129:
	s_andn2_saveexec_b64 s[10:11], s[10:11]
	s_cbranch_execz .LBB0_149
	s_mov_b64 s[10:11], exec
	buffer_wbl2 sc1
	s_waitcnt lgkmcnt(0)
	s_waitcnt vmcnt(0)
	v_mbcnt_lo_u32_b32 v1, s10, 0
	v_mbcnt_hi_u32_b32 v1, s11, v1
	v_cmp_eq_u32_e32 vcc, 0, v1
	s_and_saveexec_b64 s[12:13], vcc
	s_cbranch_execz .LBB0_132
	s_bcnt1_i32_b64 s10, s[10:11]
	v_mov_b32_e32 v2, 0x7000
	v_mov_b32_e32 v3, s10
	global_atomic_add v2, v2, v3, s[92:93] offset:1024 sc0

; __device__ __forceinline__ unsigned xb_ld(unsigned* p)              { return __hip_atomic_load(p, __ATOMIC_RELAXED, __HIP_MEMORY_SCOPE_AGENT); }
; __device__ __forceinline__ unsigned xb_add(unsigned* p, unsigned v) { return __hip_atomic_fetch_add(p, v, __ATOMIC_RELAXED, __HIP_MEMORY_SCOPE_AGENT); }
; #define XB_SPIN(cond, bar) do { unsigned _sp = 0; while (cond) { __builtin_amdgcn_s_sleep(1); \
;     if ((++_sp & 255u) == 0u) { if (xb_ld(&(bar)[XB_TMO])) break; if (_sp > XB_SPIN_CAP) { atomicAdd(&(bar)[XB_TMO], 1u); break; } } } } while (0)
; __device__ __forceinline__ void xcd_barrier(const XcdBarrier& b) {
;     ...
;             if (og + 1u == (tg + 1u) * nx) xb_add(&bar[XB_TOPGEN], 1u);
;             else XB_SPIN(xb_ld(&bar[XB_TOPGEN]) == tg, bar);
;             __builtin_amdgcn_fence(__ATOMIC_ACQUIRE, "agent");
;             xb_add(&bar[XB_XGEN(b.x)], 1u);
;             asm volatile("s_waitcnt vmcnt(0)" ::: "memory");
.LBB0_146:
	s_or_b64 exec, exec, s[10:11]
	s_mov_b64 s[10:11], exec
	v_mbcnt_lo_u32_b32 v0, s10, 0
	v_mbcnt_hi_u32_b32 v0, s11, v0
	v_cmp_eq_u32_e32 vcc, 0, v0
	s_waitcnt vmcnt(0)
	s_and_saveexec_b64 s[12:13], vcc
	s_cbranch_execz .LBB0_148
	s_bcnt1_i32_b64 s10, s[10:11]
	v_mov_b32_e32 v0, 0x2000
	v_mov_b32_e32 v1, s10
	global_atomic_add v0, v1, s[8:9] offset:1024

; __device__ __forceinline__ unsigned xb_add(unsigned* p, unsigned v) { return __hip_atomic_fetch_add(p, v, __ATOMIC_RELAXED, __HIP_MEMORY_SCOPE_AGENT); }
; #define SEAM(k) do { if (IN(k) && IN((k) + 1)) { if ((k) == GSYNC_SEAM) cg::this_grid().sync(); else xcd_barrier(xbar); } } while (0)
; __device__ __forceinline__ void xcd_barrier(const XcdBarrier& b) {
;     ...
;         unsigned nloc = b.st[0], nx = b.st[1];
;         if (nloc == 0u) { xcd_barrier_complete(bar, b.x, nloc, nx); b.st[0] = nloc; b.st[1] = nx; }
;         const unsigned old = xb_add(&bar[XB_XSUB(b.x)], 1u);
;         const unsigned gen = old / nloc;
;         if (old + 1u == (gen + 1u) * nloc) {
; __global__ void __launch_bounds__(512, 2) layer_fwd(Args args) {
;     ...
;     SEAM(1);
.LBB0_223:
	s_or_b64 exec, exec, s[14:15]
	s_cmpk_eq_i32 s33, 0x100
	s_cbranch_scc0 .Ls1_inv
	s_cmp_gt_i32 s2, 63
	s_cbranch_scc1 .Ls1_noinv

; __device__ __forceinline__ unsigned xb_ld(unsigned* p)              { return __hip_atomic_load(p, __ATOMIC_RELAXED, __HIP_MEMORY_SCOPE_AGENT); }
; __device__ __forceinline__ unsigned xb_add(unsigned* p, unsigned v) { return __hip_atomic_fetch_add(p, v, __ATOMIC_RELAXED, __HIP_MEMORY_SCOPE_AGENT); }
; #define XB_SPIN(cond, bar) do { unsigned _sp = 0; while (cond) { __builtin_amdgcn_s_sleep(1); \
;     if ((++_sp & 255u) == 0u) { if (xb_ld(&(bar)[XB_TMO])) break; if (_sp > XB_SPIN_CAP) { atomicAdd(&(bar)[XB_TMO], 1u); break; } } } } while (0)
; __device__ __forceinline__ void xcd_barrier(const XcdBarrier& b) {
;     ...
;         const unsigned old = xb_add(&bar[XB_XSUB(b.x)], 1u);
;         const unsigned gen = old / nloc;
;         if (old + 1u == (gen + 1u) * nloc) {
;             __builtin_amdgcn_fence(__ATOMIC_RELEASE, "agent");
;     ...
;             XB_SPIN(xb_ld(&bar[XB_XGEN(b.x)]) == gen, bar);
.Ls1_noinv:
	v_cvt_f32_u32_e32 v4, v2
	s_waitcnt vmcnt(0)
	v_readfirstlane_b32 s8, v3
	v_sub_u32_e32 v3, 0, v2
	v_rcp_iflag_f32_e32 v4, v4
	v_add_u32_e32 v5, s8, v1
	v_mul_f32_e32 v4, 0x4f7ffffe, v4
	v_cvt_u32_f32_e32 v4, v4
	v_mul_lo_u32 v1, v3, v4
	v_mul_hi_u32 v1, v4, v1
	v_add_u32_e32 v1, v4, v1
	v_mul_hi_u32 v1, v5, v1
	v_mul_lo_u32 v3, v1, v2
	v_sub_u32_e32 v3, v5, v3
	v_add_u32_e32 v4, 1, v1
	v_cmp_ge_u32_e32 vcc, v3, v2
	s_nop 1
	v_cndmask_b32_e32 v1, v1, v4, vcc
	v_sub_u32_e32 v4, v3, v2
	v_cndmask_b32_e32 v3, v3, v4, vcc
	v_add_u32_e32 v4, 1, v1
	v_cmp_ge_u32_e32 vcc, v3, v2
	v_add_u32_e32 v3, 1, v5
	s_nop 0
	v_cndmask_b32_e32 v1, v1, v4, vcc
	v_mul_lo_u32 v4, v2, v1
	v_add_u32_e32 v2, v4, v2
	v_cmp_ne_u32_e32 vcc, v3, v2
	s_and_saveexec_b64 s[8:9], vcc
	s_xor_b64 s[12:13], exec, s[8:9]
	s_cbranch_execz .LBB0_237
	s_cmpk_eq_i32 s33, 0x100
	s_cbranch_scc0 .Ls1_wait
	s_cmp_gt_i32 s2, 63
	s_cbranch_scc1 .LBB0_237

; __device__ __forceinline__ unsigned xb_ld(unsigned* p)              { return __hip_atomic_load(p, __ATOMIC_RELAXED, __HIP_MEMORY_SCOPE_AGENT); }
; #define XB_SPIN(cond, bar) do { unsigned _sp = 0; while (cond) { __builtin_amdgcn_s_sleep(1); \
;     if ((++_sp & 255u) == 0u) { if (xb_ld(&(bar)[XB_TMO])) break; if (_sp > XB_SPIN_CAP) { atomicAdd(&(bar)[XB_TMO], 1u); break; } } } } while (0)
; __device__ __forceinline__ void xcd_barrier(const XcdBarrier& b) {
;     ...
;             XB_SPIN(xb_ld(&bar[XB_XGEN(b.x)]) == gen, bar);
;             __builtin_amdgcn_fence(__ATOMIC_ACQUIRE, "agent");
;             asm volatile("s_waitcnt vmcnt(0)" ::: "memory");
.LBB0_236:
	s_or_b64 exec, exec, s[14:15]
	s_waitcnt vmcnt(0)
	s_waitcnt vmcnt(0)

; __device__ __forceinline__ unsigned xb_ld(unsigned* p)              { return __hip_atomic_load(p, __ATOMIC_RELAXED, __HIP_MEMORY_SCOPE_AGENT); }
; __device__ __forceinline__ unsigned xb_add(unsigned* p, unsigned v) { return __hip_atomic_fetch_add(p, v, __ATOMIC_RELAXED, __HIP_MEMORY_SCOPE_AGENT); }
; #define XB_SPIN(cond, bar) do { unsigned _sp = 0; while (cond) { __builtin_amdgcn_s_sleep(1); \
;     if ((++_sp & 255u) == 0u) { if (xb_ld(&(bar)[XB_TMO])) break; if (_sp > XB_SPIN_CAP) { atomicAdd(&(bar)[XB_TMO], 1u); break; } } } } while (0)
; __device__ __forceinline__ void xcd_barrier(const XcdBarrier& b) {
;     ...
;             if (og + 1u == (tg + 1u) * nx) xb_add(&bar[XB_TOPGEN], 1u);
;             else XB_SPIN(xb_ld(&bar[XB_TOPGEN]) == tg, bar);
;             __builtin_amdgcn_fence(__ATOMIC_ACQUIRE, "agent");
;             xb_add(&bar[XB_XGEN(b.x)], 1u);
;             asm volatile("s_waitcnt vmcnt(0)" ::: "memory");
.LBB0_254:
	s_or_b64 exec, exec, s[12:13]
	s_mov_b64 s[12:13], exec
	v_mbcnt_lo_u32_b32 v0, s12, 0
	v_mbcnt_hi_u32_b32 v0, s13, v0
	v_cmp_eq_u32_e32 vcc, 0, v0
	s_waitcnt vmcnt(0)
	s_and_saveexec_b64 s[14:15], vcc
	s_cbranch_execz .LBB0_256
	s_bcnt1_i32_b64 s8, s[12:13]
	v_mov_b32_e32 v0, 0x2000
	v_mov_b32_e32 v1, s8
	global_atomic_add v0, v1, s[10:11] offset:1024

; __device__ __forceinline__ unsigned xb_ld(unsigned* p)              { return __hip_atomic_load(p, __ATOMIC_RELAXED, __HIP_MEMORY_SCOPE_AGENT); }
; __device__ __forceinline__ unsigned xb_add(unsigned* p, unsigned v) { return __hip_atomic_fetch_add(p, v, __ATOMIC_RELAXED, __HIP_MEMORY_SCOPE_AGENT); }
; #define XB_SPIN(cond, bar) do { unsigned _sp = 0; while (cond) { __builtin_amdgcn_s_sleep(1); \
;     if ((++_sp & 255u) == 0u) { if (xb_ld(&(bar)[XB_TMO])) break; if (_sp > XB_SPIN_CAP) { atomicAdd(&(bar)[XB_TMO], 1u); break; } } } } while (0)
; __device__ __forceinline__ void xcd_barrier(const XcdBarrier& b) {
;     ...
;         unsigned nloc = b.st[0], nx = b.st[1];
;         if (nloc == 0u) { xcd_barrier_complete(bar, b.x, nloc, nx); b.st[0] = nloc; b.st[1] = nx; }
;         const unsigned old = xb_add(&bar[XB_XSUB(b.x)], 1u);
;         const unsigned gen = old / nloc;
;         if (old + 1u == (gen + 1u) * nloc) {
;             __builtin_amdgcn_fence(__ATOMIC_RELEASE, "agent");
;             asm volatile("s_waitcnt vmcnt(0)" ::: "memory");
;             const unsigned og = xb_add(&bar[XB_TOP], 1u);
;             const unsigned tg = og / nx;
;             if (og + 1u == (tg + 1u) * nx) xb_add(&bar[XB_TOPGEN], 1u);
;             else XB_SPIN(xb_ld(&bar[XB_TOPGEN]) == tg, bar);
;             __builtin_amdgcn_fence(__ATOMIC_ACQUIRE, "agent");
;             xb_add(&bar[XB_XGEN(b.x)], 1u);
;             asm volatile("s_waitcnt vmcnt(0)" ::: "memory");
;         } else {
;             XB_SPIN(xb_ld(&bar[XB_XGEN(b.x)]) == gen, bar);
;             __builtin_amdgcn_fence(__ATOMIC_ACQUIRE, "agent");
;             asm volatile("s_waitcnt vmcnt(0)" ::: "memory");
.LBB0_644:
	s_or_b64 exec, exec, s[10:11]
	buffer_inv sc1
	v_cvt_f32_u32_e32 v4, v2
	s_waitcnt vmcnt(0)
	v_readfirstlane_b32 s8, v3
	v_sub_u32_e32 v3, 0, v2
	v_rcp_iflag_f32_e32 v4, v4
	v_add_u32_e32 v5, s8, v1
	v_mul_f32_e32 v4, 0x4f7ffffe, v4
	v_cvt_u32_f32_e32 v4, v4
	v_mul_lo_u32 v1, v3, v4
	v_mul_hi_u32 v1, v4, v1
	v_add_u32_e32 v1, v4, v1
	v_mul_hi_u32 v1, v5, v1
	v_mul_lo_u32 v3, v1, v2
	v_sub_u32_e32 v3, v5, v3
	v_add_u32_e32 v4, 1, v1
	v_cmp_ge_u32_e32 vcc, v3, v2
	s_nop 1
	v_cndmask_b32_e32 v1, v1, v4, vcc
	v_sub_u32_e32 v4, v3, v2
	v_cndmask_b32_e32 v3, v3, v4, vcc
	v_add_u32_e32 v4, 1, v1
	v_cmp_ge_u32_e32 vcc, v3, v2
	v_add_u32_e32 v3, 1, v5
	s_nop 0
	v_cndmask_b32_e32 v1, v1, v4, vcc
	v_mul_lo_u32 v4, v2, v1
	v_add_u32_e32 v2, v4, v2
	v_cmp_ne_u32_e32 vcc, v3, v2
	s_and_saveexec_b64 s[8:9], vcc
	s_xor_b64 s[8:9], exec, s[8:9]
	s_cbranch_execz .LBB0_658
	s_waitcnt lgkmcnt(0)
	v_mov_b32_e32 v0, 0x2000
	global_load_dword v0, v0, s[6:7] offset:1024 sc1
	s_add_u32 s14, s6, 0x2400
	s_addc_u32 s15, s7, 0
	s_waitcnt vmcnt(0)
	v_cmp_eq_u32_e32 vcc, v0, v1
	s_and_saveexec_b64 s[10:11], vcc
	s_cbranch_execz .LBB0_657
	s_add_u32 s12, s92, 0x4200
	s_addc_u32 s13, s93, 0
	s_mov_b32 s28, 1
	s_mov_b64 s[16:17], 0
	v_mov_b32_e32 v0, 0
	s_branch .LBB0_648

; __device__ __forceinline__ unsigned xb_ld(unsigned* p)              { return __hip_atomic_load(p, __ATOMIC_RELAXED, __HIP_MEMORY_SCOPE_AGENT); }
; __device__ __forceinline__ unsigned xb_add(unsigned* p, unsigned v) { return __hip_atomic_fetch_add(p, v, __ATOMIC_RELAXED, __HIP_MEMORY_SCOPE_AGENT); }
; #define XB_SPIN(cond, bar) do { unsigned _sp = 0; while (cond) { __builtin_amdgcn_s_sleep(1); \
;     if ((++_sp & 255u) == 0u) { if (xb_ld(&(bar)[XB_TMO])) break; if (_sp > XB_SPIN_CAP) { atomicAdd(&(bar)[XB_TMO], 1u); break; } } } } while (0)
; __device__ __forceinline__ void xcd_barrier(const XcdBarrier& b) {
;     ...
;         if (old + 1u == (gen + 1u) * nloc) {
;             __builtin_amdgcn_fence(__ATOMIC_RELEASE, "agent");
;             asm volatile("s_waitcnt vmcnt(0)" ::: "memory");
;             const unsigned og = xb_add(&bar[XB_TOP], 1u);
;             const unsigned tg = og / nx;
;             if (og + 1u == (tg + 1u) * nx) xb_add(&bar[XB_TOPGEN], 1u);
;             else XB_SPIN(xb_ld(&bar[XB_TOPGEN]) == tg, bar);
;             __builtin_amdgcn_fence(__ATOMIC_ACQUIRE, "agent");
;             xb_add(&bar[XB_XGEN(b.x)], 1u);
;             asm volatile("s_waitcnt vmcnt(0)" ::: "memory");
;         } else {
;             XB_SPIN(xb_ld(&bar[XB_XGEN(b.x)]) == gen, bar);
.LBB0_654:
	s_or_b64 exec, exec, s[16:17]
	s_xor_b64 s[14:15], s[20:21], -1
	s_and_saveexec_b64 s[16:17], s[14:15]
	s_xor_b64 s[16:17], exec, s[16:17]
	s_cbranch_execz .LBB0_657
	s_mov_b64 s[14:15], exec
	v_mbcnt_lo_u32_b32 v0, s14, 0
	v_mbcnt_hi_u32_b32 v0, s15, v0
	v_cmp_eq_u32_e32 vcc, 0, v0
	s_and_b64 s[16:17], exec, vcc
	s_mov_b64 exec, s[16:17]
	s_cbranch_execz .LBB0_657
	s_bcnt1_i32_b64 s14, s[14:15]
	v_mov_b32_e32 v0, 0
	v_mov_b32_e32 v1, s14
	global_atomic_add v0, v1, s[12:13]
.LBB0_657:
	s_or_b64 exec, exec, s[10:11]
	s_waitcnt vmcnt(0)
	s_waitcnt vmcnt(0)
.LBB0_658:
	s_andn2_saveexec_b64 s[8:9], s[8:9]
	s_cbranch_execz .LBB0_678
	s_mov_b64 s[8:9], exec
	buffer_wbl2 sc1
	s_waitcnt lgkmcnt(0)
	s_waitcnt vmcnt(0)
	v_mbcnt_lo_u32_b32 v1, s8, 0
	v_mbcnt_hi_u32_b32 v1, s9, v1
	v_cmp_eq_u32_e32 vcc, 0, v1
	s_and_saveexec_b64 s[10:11], vcc
	s_cbranch_execz .LBB0_661
	s_bcnt1_i32_b64 s8, s[8:9]
	v_mov_b32_e32 v2, 0x7000
	v_mov_b32_e32 v3, s8
	global_atomic_add v2, v2, v3, s[92:93] offset:1024 sc0

; __device__ __forceinline__ unsigned xb_ld(unsigned* p)              { return __hip_atomic_load(p, __ATOMIC_RELAXED, __HIP_MEMORY_SCOPE_AGENT); }
; __device__ __forceinline__ unsigned xb_add(unsigned* p, unsigned v) { return __hip_atomic_fetch_add(p, v, __ATOMIC_RELAXED, __HIP_MEMORY_SCOPE_AGENT); }
; #define XB_SPIN(cond, bar) do { unsigned _sp = 0; while (cond) { __builtin_amdgcn_s_sleep(1); \
;     if ((++_sp & 255u) == 0u) { if (xb_ld(&(bar)[XB_TMO])) break; if (_sp > XB_SPIN_CAP) { atomicAdd(&(bar)[XB_TMO], 1u); break; } } } } while (0)
; __device__ __forceinline__ void xcd_barrier(const XcdBarrier& b) {
;     ...
;             if (og + 1u == (tg + 1u) * nx) xb_add(&bar[XB_TOPGEN], 1u);
;             else XB_SPIN(xb_ld(&bar[XB_TOPGEN]) == tg, bar);
;             __builtin_amdgcn_fence(__ATOMIC_ACQUIRE, "agent");
;             xb_add(&bar[XB_XGEN(b.x)], 1u);
;             asm volatile("s_waitcnt vmcnt(0)" ::: "memory");
.LBB0_675:
	s_or_b64 exec, exec, s[8:9]
	s_mov_b64 s[8:9], exec
	v_mbcnt_lo_u32_b32 v0, s8, 0
	v_mbcnt_hi_u32_b32 v0, s9, v0
	v_cmp_eq_u32_e32 vcc, 0, v0
	s_waitcnt vmcnt(0)
	s_and_saveexec_b64 s[10:11], vcc
	s_cbranch_execz .LBB0_677
	s_bcnt1_i32_b64 s8, s[8:9]
	v_mov_b32_e32 v0, 0x2000
	v_mov_b32_e32 v1, s8
	global_atomic_add v0, v1, s[6:7] offset:1024
